# band epilogue: gate z rows loaded as 8 dwordx4 with v_permlane16_swap instead of 16 dwordx2 (both entry paths)
# speedup vs baseline: 1.0046x; 1.0046x over previous
.LBB0_374:
	v_lshlrev_b32_e32 v125, 1, v138
	v_mad_u32_u24 v122, v192, s59, v125
	v_lshl_add_u32 v124, v192, 12, v125
	s_add_u32 s14, s4, s0
	s_addc_u32 s15, s5, s1
	s_add_u32 s14, s14, 0x1000
	s_addc_u32 s15, s15, 0
	s_add_u32 s38, s56, s0
	s_addc_u32 s39, s57, s1
	v_add_u32_e32 v123, 0x2a000, v122
	v_add_u32_e32 v125, 0x10000, v124
	v_bfe_u32 v246, v122, 3, 1
	v_mul_u32_u24_e32 v246, 24, v246
	v_add_u32_e32 v247, v123, v246
	v_add_u32_e32 v246, v122, v246
	global_load_dwordx4 v[86:89], v246, s[14:15]
	global_load_dwordx4 v[90:93], v246, s[14:15] offset:64
	global_load_dwordx4 v[94:97], v246, s[14:15] offset:128
	global_load_dwordx4 v[98:101], v246, s[14:15] offset:192
	global_load_dwordx4 v[102:105], v247, s[14:15]
	global_load_dwordx4 v[106:109], v247, s[14:15] offset:64
	global_load_dwordx4 v[110:113], v247, s[14:15] offset:128
	global_load_dwordx4 v[114:117], v247, s[14:15] offset:192
.Lband_epi_compute:
	v_bfe_u32 v246, v124, 3, 1
	v_mul_u32_u24_e32 v246, 24, v246
	v_add_u32_e32 v244, v124, v246
	v_add_u32_e32 v245, 0x10000, v244
	v_rcp_f32_e32 v118, v126
	v_rcp_f32_e32 v119, v34
	s_nop 0
	v_fma_f32 v0, -v126, v118, 1.0
	v_fma_f32 v120, -v34, v119, 1.0
	v_fmac_f32_e32 v118, v0, v118
	v_fmac_f32_e32 v119, v120, v119
	v_mov_b32_e32 v0, v118
	v_mov_b32_e32 v120, v119
	s_waitcnt vmcnt(7)
	v_permlane16_swap_b32_e32 v86, v88
	v_permlane16_swap_b32_e32 v87, v89
	v_lshlrev_b32_e32 v66, 16, v86
	v_and_b32_e32 v67, 0xffff0000, v86
	v_lshlrev_b32_e32 v68, 16, v87
	v_and_b32_e32 v69, 0xffff0000, v87
	v_mul_f32_e32 v70, 0xbfb8aa3b, v66
	v_mul_f32_e32 v71, 0xbfb8aa3b, v67
	v_mul_f32_e32 v72, 0xbfb8aa3b, v68
	v_mul_f32_e32 v73, 0xbfb8aa3b, v69
	v_exp_f32_e32 v70, v70
	v_exp_f32_e32 v71, v71
	v_exp_f32_e32 v72, v72
	v_exp_f32_e32 v73, v73
	v_pk_mul_f32 v[78:79], v[82:83], v[0:1] op_sel_hi:[1,0]
	v_pk_add_f32 v[70:71], v[70:71], 1.0 op_sel_hi:[1,0]
	v_pk_add_f32 v[72:73], v[72:73], 1.0 op_sel_hi:[1,0]
	v_rcp_f32_e32 v74, v70
	v_rcp_f32_e32 v75, v71
	v_rcp_f32_e32 v76, v72
	v_rcp_f32_e32 v77, v73
	v_pk_mul_f32 v[80:81], v[84:85], v[0:1] op_sel_hi:[1,0]
	v_pk_mul_f32 v[74:75], v[66:67], v[74:75]
	v_pk_mul_f32 v[76:77], v[68:69], v[76:77]
	v_pk_mul_f32 v[78:79], v[78:79], v[74:75]
	v_pk_mul_f32 v[80:81], v[80:81], v[76:77]
	v_cvt_pk_bf16_f32 v240, v78, v79
	v_cvt_pk_bf16_f32 v241, v80, v81
	s_waitcnt vmcnt(7)
	v_lshlrev_b32_e32 v66, 16, v88
	v_and_b32_e32 v67, 0xffff0000, v88
	v_lshlrev_b32_e32 v68, 16, v89
	v_and_b32_e32 v69, 0xffff0000, v89
	v_mul_f32_e32 v70, 0xbfb8aa3b, v66
	v_mul_f32_e32 v71, 0xbfb8aa3b, v67
	v_mul_f32_e32 v72, 0xbfb8aa3b, v68
	v_mul_f32_e32 v73, 0xbfb8aa3b, v69
	v_exp_f32_e32 v70, v70
	v_exp_f32_e32 v71, v71
	v_exp_f32_e32 v72, v72
	v_exp_f32_e32 v73, v73
	v_pk_mul_f32 v[78:79], v[62:63], v[0:1] op_sel_hi:[1,0]
	v_pk_add_f32 v[70:71], v[70:71], 1.0 op_sel_hi:[1,0]
	v_pk_add_f32 v[72:73], v[72:73], 1.0 op_sel_hi:[1,0]
	v_rcp_f32_e32 v74, v70
	v_rcp_f32_e32 v75, v71
	v_rcp_f32_e32 v76, v72
	v_rcp_f32_e32 v77, v73
	v_pk_mul_f32 v[80:81], v[64:65], v[0:1] op_sel_hi:[1,0]
	v_pk_mul_f32 v[74:75], v[66:67], v[74:75]
	v_pk_mul_f32 v[76:77], v[68:69], v[76:77]
	v_pk_mul_f32 v[78:79], v[78:79], v[74:75]
	v_pk_mul_f32 v[80:81], v[80:81], v[76:77]
	v_cvt_pk_bf16_f32 v242, v78, v79
	v_cvt_pk_bf16_f32 v243, v80, v81
	s_nop 1
	v_permlane16_swap_b32_e32 v240, v242
	v_permlane16_swap_b32_e32 v241, v243
	global_store_dwordx4 v244, v[240:243], s[38:39]
	s_waitcnt vmcnt(7)
	v_permlane16_swap_b32_e32 v90, v92
	v_permlane16_swap_b32_e32 v91, v93
	v_lshlrev_b32_e32 v66, 16, v90
	v_and_b32_e32 v67, 0xffff0000, v90
	v_lshlrev_b32_e32 v68, 16, v91
	v_and_b32_e32 v69, 0xffff0000, v91
	v_mul_f32_e32 v70, 0xbfb8aa3b, v66
	v_mul_f32_e32 v71, 0xbfb8aa3b, v67
	v_mul_f32_e32 v72, 0xbfb8aa3b, v68
	v_mul_f32_e32 v73, 0xbfb8aa3b, v69
	v_exp_f32_e32 v70, v70
	v_exp_f32_e32 v71, v71
	v_exp_f32_e32 v72, v72
	v_exp_f32_e32 v73, v73
	v_pk_mul_f32 v[78:79], v[58:59], v[0:1] op_sel_hi:[1,0]
	v_pk_add_f32 v[70:71], v[70:71], 1.0 op_sel_hi:[1,0]
	v_pk_add_f32 v[72:73], v[72:73], 1.0 op_sel_hi:[1,0]
	v_rcp_f32_e32 v74, v70
	v_rcp_f32_e32 v75, v71
	v_rcp_f32_e32 v76, v72
	v_rcp_f32_e32 v77, v73
	v_pk_mul_f32 v[80:81], v[60:61], v[0:1] op_sel_hi:[1,0]
	v_pk_mul_f32 v[74:75], v[66:67], v[74:75]
	v_pk_mul_f32 v[76:77], v[68:69], v[76:77]
	v_pk_mul_f32 v[78:79], v[78:79], v[74:75]
	v_pk_mul_f32 v[80:81], v[80:81], v[76:77]
	v_cvt_pk_bf16_f32 v240, v78, v79
	v_cvt_pk_bf16_f32 v241, v80, v81
	s_waitcnt vmcnt(7)
	v_lshlrev_b32_e32 v66, 16, v92
	v_and_b32_e32 v67, 0xffff0000, v92
	v_lshlrev_b32_e32 v68, 16, v93
	v_and_b32_e32 v69, 0xffff0000, v93
	v_mul_f32_e32 v70, 0xbfb8aa3b, v66
	v_mul_f32_e32 v71, 0xbfb8aa3b, v67
	v_mul_f32_e32 v72, 0xbfb8aa3b, v68
	v_mul_f32_e32 v73, 0xbfb8aa3b, v69
	v_exp_f32_e32 v70, v70
	v_exp_f32_e32 v71, v71
	v_exp_f32_e32 v72, v72
	v_exp_f32_e32 v73, v73
	v_pk_mul_f32 v[78:79], v[54:55], v[0:1] op_sel_hi:[1,0]
	v_pk_add_f32 v[70:71], v[70:71], 1.0 op_sel_hi:[1,0]
	v_pk_add_f32 v[72:73], v[72:73], 1.0 op_sel_hi:[1,0]
	v_rcp_f32_e32 v74, v70
	v_rcp_f32_e32 v75, v71
	v_rcp_f32_e32 v76, v72
	v_rcp_f32_e32 v77, v73
	v_pk_mul_f32 v[80:81], v[56:57], v[0:1] op_sel_hi:[1,0]
	v_pk_mul_f32 v[74:75], v[66:67], v[74:75]
	v_pk_mul_f32 v[76:77], v[68:69], v[76:77]
	v_pk_mul_f32 v[78:79], v[78:79], v[74:75]
	v_pk_mul_f32 v[80:81], v[80:81], v[76:77]
	v_cvt_pk_bf16_f32 v242, v78, v79
	v_cvt_pk_bf16_f32 v243, v80, v81
	s_nop 1
	v_permlane16_swap_b32_e32 v240, v242
	v_permlane16_swap_b32_e32 v241, v243
	global_store_dwordx4 v244, v[240:243], s[38:39] offset:64
	s_waitcnt vmcnt(7)
	v_permlane16_swap_b32_e32 v94, v96
	v_permlane16_swap_b32_e32 v95, v97
	v_lshlrev_b32_e32 v66, 16, v94
	v_and_b32_e32 v67, 0xffff0000, v94
	v_lshlrev_b32_e32 v68, 16, v95
	v_and_b32_e32 v69, 0xffff0000, v95
	v_mul_f32_e32 v70, 0xbfb8aa3b, v66
	v_mul_f32_e32 v71, 0xbfb8aa3b, v67
	v_mul_f32_e32 v72, 0xbfb8aa3b, v68
	v_mul_f32_e32 v73, 0xbfb8aa3b, v69
	v_exp_f32_e32 v70, v70
	v_exp_f32_e32 v71, v71
	v_exp_f32_e32 v72, v72
	v_exp_f32_e32 v73, v73
	v_pk_mul_f32 v[78:79], v[50:51], v[0:1] op_sel_hi:[1,0]
	v_pk_add_f32 v[70:71], v[70:71], 1.0 op_sel_hi:[1,0]
	v_pk_add_f32 v[72:73], v[72:73], 1.0 op_sel_hi:[1,0]
	v_rcp_f32_e32 v74, v70
	v_rcp_f32_e32 v75, v71
	v_rcp_f32_e32 v76, v72
	v_rcp_f32_e32 v77, v73
	v_pk_mul_f32 v[80:81], v[52:53], v[0:1] op_sel_hi:[1,0]
	v_pk_mul_f32 v[74:75], v[66:67], v[74:75]
	v_pk_mul_f32 v[76:77], v[68:69], v[76:77]
	v_pk_mul_f32 v[78:79], v[78:79], v[74:75]
	v_pk_mul_f32 v[80:81], v[80:81], v[76:77]
	v_cvt_pk_bf16_f32 v240, v78, v79
	v_cvt_pk_bf16_f32 v241, v80, v81
	s_waitcnt vmcnt(7)
	v_lshlrev_b32_e32 v66, 16, v96
	v_and_b32_e32 v67, 0xffff0000, v96
	v_lshlrev_b32_e32 v68, 16, v97
	v_and_b32_e32 v69, 0xffff0000, v97
	v_mul_f32_e32 v70, 0xbfb8aa3b, v66
	v_mul_f32_e32 v71, 0xbfb8aa3b, v67
	v_mul_f32_e32 v72, 0xbfb8aa3b, v68
	v_mul_f32_e32 v73, 0xbfb8aa3b, v69
	v_exp_f32_e32 v70, v70
	v_exp_f32_e32 v71, v71
	v_exp_f32_e32 v72, v72
	v_exp_f32_e32 v73, v73
	v_pk_mul_f32 v[78:79], v[46:47], v[0:1] op_sel_hi:[1,0]
	v_pk_add_f32 v[70:71], v[70:71], 1.0 op_sel_hi:[1,0]
	v_pk_add_f32 v[72:73], v[72:73], 1.0 op_sel_hi:[1,0]
	v_rcp_f32_e32 v74, v70
	v_rcp_f32_e32 v75, v71
	v_rcp_f32_e32 v76, v72
	v_rcp_f32_e32 v77, v73
	v_pk_mul_f32 v[80:81], v[48:49], v[0:1] op_sel_hi:[1,0]
	v_pk_mul_f32 v[74:75], v[66:67], v[74:75]
	v_pk_mul_f32 v[76:77], v[68:69], v[76:77]
	v_pk_mul_f32 v[78:79], v[78:79], v[74:75]
	v_pk_mul_f32 v[80:81], v[80:81], v[76:77]
	v_cvt_pk_bf16_f32 v242, v78, v79
	v_cvt_pk_bf16_f32 v243, v80, v81
	s_nop 1
	v_permlane16_swap_b32_e32 v240, v242
	v_permlane16_swap_b32_e32 v241, v243
	global_store_dwordx4 v244, v[240:243], s[38:39] offset:128
	s_waitcnt vmcnt(7)
	v_permlane16_swap_b32_e32 v98, v100
	v_permlane16_swap_b32_e32 v99, v101
	v_lshlrev_b32_e32 v66, 16, v98
	v_and_b32_e32 v67, 0xffff0000, v98
	v_lshlrev_b32_e32 v68, 16, v99
	v_and_b32_e32 v69, 0xffff0000, v99
	v_mul_f32_e32 v70, 0xbfb8aa3b, v66
	v_mul_f32_e32 v71, 0xbfb8aa3b, v67
	v_mul_f32_e32 v72, 0xbfb8aa3b, v68
	v_mul_f32_e32 v73, 0xbfb8aa3b, v69
	v_exp_f32_e32 v70, v70
	v_exp_f32_e32 v71, v71
	v_exp_f32_e32 v72, v72
	v_exp_f32_e32 v73, v73
	v_pk_mul_f32 v[78:79], v[42:43], v[0:1] op_sel_hi:[1,0]
	v_pk_add_f32 v[70:71], v[70:71], 1.0 op_sel_hi:[1,0]
	v_pk_add_f32 v[72:73], v[72:73], 1.0 op_sel_hi:[1,0]
	v_rcp_f32_e32 v74, v70
	v_rcp_f32_e32 v75, v71
	v_rcp_f32_e32 v76, v72
	v_rcp_f32_e32 v77, v73
	v_pk_mul_f32 v[80:81], v[44:45], v[0:1] op_sel_hi:[1,0]
	v_pk_mul_f32 v[74:75], v[66:67], v[74:75]
	v_pk_mul_f32 v[76:77], v[68:69], v[76:77]
	v_pk_mul_f32 v[78:79], v[78:79], v[74:75]
	v_pk_mul_f32 v[80:81], v[80:81], v[76:77]
	v_cvt_pk_bf16_f32 v240, v78, v79
	v_cvt_pk_bf16_f32 v241, v80, v81
	s_waitcnt vmcnt(7)
	v_lshlrev_b32_e32 v66, 16, v100
	v_and_b32_e32 v67, 0xffff0000, v100
	v_lshlrev_b32_e32 v68, 16, v101
	v_and_b32_e32 v69, 0xffff0000, v101
	v_mul_f32_e32 v70, 0xbfb8aa3b, v66
	v_mul_f32_e32 v71, 0xbfb8aa3b, v67
	v_mul_f32_e32 v72, 0xbfb8aa3b, v68
	v_mul_f32_e32 v73, 0xbfb8aa3b, v69
	v_exp_f32_e32 v70, v70
	v_exp_f32_e32 v71, v71
	v_exp_f32_e32 v72, v72
	v_exp_f32_e32 v73, v73
	v_pk_mul_f32 v[78:79], v[38:39], v[0:1] op_sel_hi:[1,0]
	v_pk_add_f32 v[70:71], v[70:71], 1.0 op_sel_hi:[1,0]
	v_pk_add_f32 v[72:73], v[72:73], 1.0 op_sel_hi:[1,0]
	v_rcp_f32_e32 v74, v70
	v_rcp_f32_e32 v75, v71
	v_rcp_f32_e32 v76, v72
	v_rcp_f32_e32 v77, v73
	v_pk_mul_f32 v[80:81], v[40:41], v[0:1] op_sel_hi:[1,0]
	v_pk_mul_f32 v[74:75], v[66:67], v[74:75]
	v_pk_mul_f32 v[76:77], v[68:69], v[76:77]
	v_pk_mul_f32 v[78:79], v[78:79], v[74:75]
	v_pk_mul_f32 v[80:81], v[80:81], v[76:77]
	v_cvt_pk_bf16_f32 v242, v78, v79
	v_cvt_pk_bf16_f32 v243, v80, v81
	s_nop 1
	v_permlane16_swap_b32_e32 v240, v242
	v_permlane16_swap_b32_e32 v241, v243
	global_store_dwordx4 v244, v[240:243], s[38:39] offset:192
	s_waitcnt vmcnt(7)
	v_permlane16_swap_b32_e32 v102, v104
	v_permlane16_swap_b32_e32 v103, v105
	v_lshlrev_b32_e32 v66, 16, v102
	v_and_b32_e32 v67, 0xffff0000, v102
	v_lshlrev_b32_e32 v68, 16, v103
	v_and_b32_e32 v69, 0xffff0000, v103
	v_mul_f32_e32 v70, 0xbfb8aa3b, v66
	v_mul_f32_e32 v71, 0xbfb8aa3b, v67
	v_mul_f32_e32 v72, 0xbfb8aa3b, v68
	v_mul_f32_e32 v73, 0xbfb8aa3b, v69
	v_exp_f32_e32 v70, v70
	v_exp_f32_e32 v71, v71
	v_exp_f32_e32 v72, v72
	v_exp_f32_e32 v73, v73
	v_pk_mul_f32 v[78:79], v[30:31], v[120:121] op_sel_hi:[1,0]
	v_pk_add_f32 v[70:71], v[70:71], 1.0 op_sel_hi:[1,0]
	v_pk_add_f32 v[72:73], v[72:73], 1.0 op_sel_hi:[1,0]
	v_rcp_f32_e32 v74, v70
	v_rcp_f32_e32 v75, v71
	v_rcp_f32_e32 v76, v72
	v_rcp_f32_e32 v77, v73
	v_pk_mul_f32 v[80:81], v[32:33], v[120:121] op_sel_hi:[1,0]
	v_pk_mul_f32 v[74:75], v[66:67], v[74:75]
	v_pk_mul_f32 v[76:77], v[68:69], v[76:77]
	v_pk_mul_f32 v[78:79], v[78:79], v[74:75]
	v_pk_mul_f32 v[80:81], v[80:81], v[76:77]
	v_cvt_pk_bf16_f32 v240, v78, v79
	v_cvt_pk_bf16_f32 v241, v80, v81
	s_waitcnt vmcnt(7)
	v_lshlrev_b32_e32 v66, 16, v104
	v_and_b32_e32 v67, 0xffff0000, v104
	v_lshlrev_b32_e32 v68, 16, v105
	v_and_b32_e32 v69, 0xffff0000, v105
	v_mul_f32_e32 v70, 0xbfb8aa3b, v66
	v_mul_f32_e32 v71, 0xbfb8aa3b, v67
	v_mul_f32_e32 v72, 0xbfb8aa3b, v68
	v_mul_f32_e32 v73, 0xbfb8aa3b, v69
	v_exp_f32_e32 v70, v70
	v_exp_f32_e32 v71, v71
	v_exp_f32_e32 v72, v72
	v_exp_f32_e32 v73, v73
	v_pk_mul_f32 v[78:79], v[26:27], v[120:121] op_sel_hi:[1,0]
	v_pk_add_f32 v[70:71], v[70:71], 1.0 op_sel_hi:[1,0]
	v_pk_add_f32 v[72:73], v[72:73], 1.0 op_sel_hi:[1,0]
	v_rcp_f32_e32 v74, v70
	v_rcp_f32_e32 v75, v71
	v_rcp_f32_e32 v76, v72
	v_rcp_f32_e32 v77, v73
	v_pk_mul_f32 v[80:81], v[28:29], v[120:121] op_sel_hi:[1,0]
	v_pk_mul_f32 v[74:75], v[66:67], v[74:75]
	v_pk_mul_f32 v[76:77], v[68:69], v[76:77]
	v_pk_mul_f32 v[78:79], v[78:79], v[74:75]
	v_pk_mul_f32 v[80:81], v[80:81], v[76:77]
	v_cvt_pk_bf16_f32 v242, v78, v79
	v_cvt_pk_bf16_f32 v243, v80, v81
	s_nop 1
	v_permlane16_swap_b32_e32 v240, v242
	v_permlane16_swap_b32_e32 v241, v243
	global_store_dwordx4 v245, v[240:243], s[38:39]
	s_waitcnt vmcnt(7)
	v_permlane16_swap_b32_e32 v106, v108
	v_permlane16_swap_b32_e32 v107, v109
	v_lshlrev_b32_e32 v66, 16, v106
	v_and_b32_e32 v67, 0xffff0000, v106
	v_lshlrev_b32_e32 v68, 16, v107
	v_and_b32_e32 v69, 0xffff0000, v107
	v_mul_f32_e32 v70, 0xbfb8aa3b, v66
	v_mul_f32_e32 v71, 0xbfb8aa3b, v67
	v_mul_f32_e32 v72, 0xbfb8aa3b, v68
	v_mul_f32_e32 v73, 0xbfb8aa3b, v69
	v_exp_f32_e32 v70, v70
	v_exp_f32_e32 v71, v71
	v_exp_f32_e32 v72, v72
	v_exp_f32_e32 v73, v73
	v_pk_mul_f32 v[78:79], v[22:23], v[120:121] op_sel_hi:[1,0]
	v_pk_add_f32 v[70:71], v[70:71], 1.0 op_sel_hi:[1,0]
	v_pk_add_f32 v[72:73], v[72:73], 1.0 op_sel_hi:[1,0]
	v_rcp_f32_e32 v74, v70
	v_rcp_f32_e32 v75, v71
	v_rcp_f32_e32 v76, v72
	v_rcp_f32_e32 v77, v73
	v_pk_mul_f32 v[80:81], v[24:25], v[120:121] op_sel_hi:[1,0]
	v_pk_mul_f32 v[74:75], v[66:67], v[74:75]
	v_pk_mul_f32 v[76:77], v[68:69], v[76:77]
	v_pk_mul_f32 v[78:79], v[78:79], v[74:75]
	v_pk_mul_f32 v[80:81], v[80:81], v[76:77]
	v_cvt_pk_bf16_f32 v240, v78, v79
	v_cvt_pk_bf16_f32 v241, v80, v81
	s_waitcnt vmcnt(7)
	v_lshlrev_b32_e32 v66, 16, v108
	v_and_b32_e32 v67, 0xffff0000, v108
	v_lshlrev_b32_e32 v68, 16, v109
	v_and_b32_e32 v69, 0xffff0000, v109
	v_mul_f32_e32 v70, 0xbfb8aa3b, v66
	v_mul_f32_e32 v71, 0xbfb8aa3b, v67
	v_mul_f32_e32 v72, 0xbfb8aa3b, v68
	v_mul_f32_e32 v73, 0xbfb8aa3b, v69
	v_exp_f32_e32 v70, v70
	v_exp_f32_e32 v71, v71
	v_exp_f32_e32 v72, v72
	v_exp_f32_e32 v73, v73
	v_pk_mul_f32 v[78:79], v[18:19], v[120:121] op_sel_hi:[1,0]
	v_pk_add_f32 v[70:71], v[70:71], 1.0 op_sel_hi:[1,0]
	v_pk_add_f32 v[72:73], v[72:73], 1.0 op_sel_hi:[1,0]
	v_rcp_f32_e32 v74, v70
	v_rcp_f32_e32 v75, v71
	v_rcp_f32_e32 v76, v72
	v_rcp_f32_e32 v77, v73
	v_pk_mul_f32 v[80:81], v[20:21], v[120:121] op_sel_hi:[1,0]
	v_pk_mul_f32 v[74:75], v[66:67], v[74:75]
	v_pk_mul_f32 v[76:77], v[68:69], v[76:77]
	v_pk_mul_f32 v[78:79], v[78:79], v[74:75]
	v_pk_mul_f32 v[80:81], v[80:81], v[76:77]
	v_cvt_pk_bf16_f32 v242, v78, v79
	v_cvt_pk_bf16_f32 v243, v80, v81
	s_nop 1
	v_permlane16_swap_b32_e32 v240, v242
	v_permlane16_swap_b32_e32 v241, v243
	global_store_dwordx4 v245, v[240:243], s[38:39] offset:64
	s_waitcnt vmcnt(7)
	v_permlane16_swap_b32_e32 v110, v112
	v_permlane16_swap_b32_e32 v111, v113
	v_lshlrev_b32_e32 v66, 16, v110
	v_and_b32_e32 v67, 0xffff0000, v110
	v_lshlrev_b32_e32 v68, 16, v111
	v_and_b32_e32 v69, 0xffff0000, v111
	v_mul_f32_e32 v70, 0xbfb8aa3b, v66
	v_mul_f32_e32 v71, 0xbfb8aa3b, v67
	v_mul_f32_e32 v72, 0xbfb8aa3b, v68
	v_mul_f32_e32 v73, 0xbfb8aa3b, v69
	v_exp_f32_e32 v70, v70
	v_exp_f32_e32 v71, v71
	v_exp_f32_e32 v72, v72
	v_exp_f32_e32 v73, v73
	v_pk_mul_f32 v[78:79], v[14:15], v[120:121] op_sel_hi:[1,0]
	v_pk_add_f32 v[70:71], v[70:71], 1.0 op_sel_hi:[1,0]
	v_pk_add_f32 v[72:73], v[72:73], 1.0 op_sel_hi:[1,0]
	v_rcp_f32_e32 v74, v70
	v_rcp_f32_e32 v75, v71
	v_rcp_f32_e32 v76, v72
	v_rcp_f32_e32 v77, v73
	v_pk_mul_f32 v[80:81], v[16:17], v[120:121] op_sel_hi:[1,0]
	v_pk_mul_f32 v[74:75], v[66:67], v[74:75]
	v_pk_mul_f32 v[76:77], v[68:69], v[76:77]
	v_pk_mul_f32 v[78:79], v[78:79], v[74:75]
	v_pk_mul_f32 v[80:81], v[80:81], v[76:77]
	v_cvt_pk_bf16_f32 v240, v78, v79
	v_cvt_pk_bf16_f32 v241, v80, v81
	s_waitcnt vmcnt(7)
	v_lshlrev_b32_e32 v66, 16, v112
	v_and_b32_e32 v67, 0xffff0000, v112
	v_lshlrev_b32_e32 v68, 16, v113
	v_and_b32_e32 v69, 0xffff0000, v113
	v_mul_f32_e32 v70, 0xbfb8aa3b, v66
	v_mul_f32_e32 v71, 0xbfb8aa3b, v67
	v_mul_f32_e32 v72, 0xbfb8aa3b, v68
	v_mul_f32_e32 v73, 0xbfb8aa3b, v69
	v_exp_f32_e32 v70, v70
	v_exp_f32_e32 v71, v71
	v_exp_f32_e32 v72, v72
	v_exp_f32_e32 v73, v73
	v_pk_mul_f32 v[78:79], v[10:11], v[120:121] op_sel_hi:[1,0]
	v_pk_add_f32 v[70:71], v[70:71], 1.0 op_sel_hi:[1,0]
	v_pk_add_f32 v[72:73], v[72:73], 1.0 op_sel_hi:[1,0]
	v_rcp_f32_e32 v74, v70
	v_rcp_f32_e32 v75, v71
	v_rcp_f32_e32 v76, v72
	v_rcp_f32_e32 v77, v73
	v_pk_mul_f32 v[80:81], v[12:13], v[120:121] op_sel_hi:[1,0]
	v_pk_mul_f32 v[74:75], v[66:67], v[74:75]
	v_pk_mul_f32 v[76:77], v[68:69], v[76:77]
	v_pk_mul_f32 v[78:79], v[78:79], v[74:75]
	v_pk_mul_f32 v[80:81], v[80:81], v[76:77]
	v_cvt_pk_bf16_f32 v242, v78, v79
	v_cvt_pk_bf16_f32 v243, v80, v81
	s_nop 1
	v_permlane16_swap_b32_e32 v240, v242
	v_permlane16_swap_b32_e32 v241, v243
	global_store_dwordx4 v245, v[240:243], s[38:39] offset:128
	s_waitcnt vmcnt(7)
	v_permlane16_swap_b32_e32 v114, v116
	v_permlane16_swap_b32_e32 v115, v117
	v_lshlrev_b32_e32 v66, 16, v114
	v_and_b32_e32 v67, 0xffff0000, v114
	v_lshlrev_b32_e32 v68, 16, v115
	v_and_b32_e32 v69, 0xffff0000, v115
	v_mul_f32_e32 v70, 0xbfb8aa3b, v66
	v_mul_f32_e32 v71, 0xbfb8aa3b, v67
	v_mul_f32_e32 v72, 0xbfb8aa3b, v68
	v_mul_f32_e32 v73, 0xbfb8aa3b, v69
	v_exp_f32_e32 v70, v70
	v_exp_f32_e32 v71, v71
	v_exp_f32_e32 v72, v72
	v_exp_f32_e32 v73, v73
	v_pk_mul_f32 v[78:79], v[6:7], v[120:121] op_sel_hi:[1,0]
	v_pk_add_f32 v[70:71], v[70:71], 1.0 op_sel_hi:[1,0]
	v_pk_add_f32 v[72:73], v[72:73], 1.0 op_sel_hi:[1,0]
	v_rcp_f32_e32 v74, v70
	v_rcp_f32_e32 v75, v71
	v_rcp_f32_e32 v76, v72
	v_rcp_f32_e32 v77, v73
	v_pk_mul_f32 v[80:81], v[8:9], v[120:121] op_sel_hi:[1,0]
	v_pk_mul_f32 v[74:75], v[66:67], v[74:75]
	v_pk_mul_f32 v[76:77], v[68:69], v[76:77]
	v_pk_mul_f32 v[78:79], v[78:79], v[74:75]
	v_pk_mul_f32 v[80:81], v[80:81], v[76:77]
	v_cvt_pk_bf16_f32 v240, v78, v79
	v_cvt_pk_bf16_f32 v241, v80, v81
	s_waitcnt vmcnt(7)
	v_lshlrev_b32_e32 v66, 16, v116
	v_and_b32_e32 v67, 0xffff0000, v116
	v_lshlrev_b32_e32 v68, 16, v117
	v_and_b32_e32 v69, 0xffff0000, v117
	v_mul_f32_e32 v70, 0xbfb8aa3b, v66
	v_mul_f32_e32 v71, 0xbfb8aa3b, v67
	v_mul_f32_e32 v72, 0xbfb8aa3b, v68
	v_mul_f32_e32 v73, 0xbfb8aa3b, v69
	v_exp_f32_e32 v70, v70
	v_exp_f32_e32 v71, v71
	v_exp_f32_e32 v72, v72
	v_exp_f32_e32 v73, v73
	v_pk_mul_f32 v[78:79], v[2:3], v[120:121] op_sel_hi:[1,0]
	v_pk_add_f32 v[70:71], v[70:71], 1.0 op_sel_hi:[1,0]
	v_pk_add_f32 v[72:73], v[72:73], 1.0 op_sel_hi:[1,0]
	v_rcp_f32_e32 v74, v70
	v_rcp_f32_e32 v75, v71
	v_rcp_f32_e32 v76, v72
	v_rcp_f32_e32 v77, v73
	v_pk_mul_f32 v[80:81], v[4:5], v[120:121] op_sel_hi:[1,0]
	v_pk_mul_f32 v[74:75], v[66:67], v[74:75]
	v_pk_mul_f32 v[76:77], v[68:69], v[76:77]
	v_pk_mul_f32 v[78:79], v[78:79], v[74:75]
	v_pk_mul_f32 v[80:81], v[80:81], v[76:77]
	v_cvt_pk_bf16_f32 v242, v78, v79
	v_cvt_pk_bf16_f32 v243, v80, v81
	s_nop 1
	v_permlane16_swap_b32_e32 v240, v242
	v_permlane16_swap_b32_e32 v241, v243
	global_store_dwordx4 v245, v[240:243], s[38:39] offset:192
	v_readlane_b32 s0, v236, 9
	s_add_i32 s40, s40, s0
	v_readlane_b32 s1, v236, 10
	s_cmpk_gt_i32 s40, 0xff
	s_cbranch_scc1 .LBB0_401

.Lband_exit:
	v_mov_b32_e32 v138, v216
	v_lshlrev_b32_e32 v125, 1, v138
	v_mad_u32_u24 v122, v192, s59, v125
	v_lshl_add_u32 v124, v192, 12, v125
	s_add_u32 s14, s4, s0
	s_addc_u32 s15, s5, s1
	s_add_u32 s14, s14, 0x1000
	s_addc_u32 s15, s15, 0
	s_add_u32 s38, s56, s0
	s_addc_u32 s39, s57, s1
	v_add_u32_e32 v123, 0x2a000, v122
	v_add_u32_e32 v125, 0x10000, v124
	v_bfe_u32 v138, v122, 3, 1
	v_mul_u32_u24_e32 v138, 24, v138
	v_add_u32_e32 v246, v122, v138
	v_add_u32_e32 v247, v123, v138
	global_load_dwordx4 v[86:89], v246, s[14:15]
	global_load_dwordx4 v[90:93], v246, s[14:15] offset:64
	global_load_dwordx4 v[94:97], v246, s[14:15] offset:128
	global_load_dwordx4 v[98:101], v246, s[14:15] offset:192
	global_load_dwordx4 v[102:105], v247, s[14:15]
	global_load_dwordx4 v[106:109], v247, s[14:15] offset:64
	global_load_dwordx4 v[110:113], v247, s[14:15] offset:128
	global_load_dwordx4 v[114:117], v247, s[14:15] offset:192
	s_barrier
	s_branch .Lband_epi_compute
